# rw_prep: hand-scheduled LoRA MFMA section + vectorised AL tile fill
# baseline (speedup 1.0000x reference)
; DEVINL u16 f2bf(float a) { return (u16)(pk2(a, 0.f) & 0xffffu); }
; DEVINL float bf2f(u16 h) { return __uint_as_float(((unsigned)h) << 16); }
; DEVINL float sigm(float x) { return 1.f / (1.f + __expf(-x)); }
; DEVINL float tanh_(float x) { return 1.f - 2.f / (__expf(2.f * x) + 1.f); }
; DEVINL float rw_shift2(const char* colsb, float muv, unsigned o, int s) {
;   const unsigned op = (s > 0) ? o - (unsigned)(NCP * 2) : o;
;   const unsigned on = (s < S_ - 1) ? o + (unsigned)(NCP * 2) : o;
;   float cur = bf2f(*(const u16*)(colsb + o));
;   float prv = bf2f(*(const u16*)(colsb + op));
;   float nxt = bf2f(*(const u16*)(colsb + on));
;   if (s == 0) prv = 0.f;
;   if (s == S_ - 1) nxt = 0.f;
;   return cur + muv * (0.5f * (prv + nxt) - cur);
; }
; DEVINL void rw_prep_unit(const Params& p, int unit) {
;     ...
; #pragma unroll 5
;   for (int idx = tid; idx < 32 * 320; idx += 512) {
;     int i = idx / 320, j = idx % 320;
;     int t = tok0 + i; int s = t & (S_ - 1);
;     unsigned o = ((unsigned)t * (unsigned)NCP + (unsigned)(C_RW + 3072 + j)) * 2u;
;     float v = rw_shift2(colsb, p.rw_mu[3072 + j], o, s);
;     if (j < 128) v = tanh_(v);
;     else if (j >= 192) v = sigm(v);
;     AL[i * 328 + j] = f2bf(v);
;   }
.LBB0_336:
	v_mov_b32_e32 v2, v189
	s_lshl_b32 s52, s51, 5
	v_mul_u32_u24_e32 v10, 0xcccd, v2
	v_lshrrev_b32_e32 v10, 22, v10
	v_mul_u32_u24_e32 v101, 0x50, v10
	v_sub_u32_e32 v11, v2, v101
	v_add_u32_e32 v101, s52, v10
	v_and_b32_e32 v12, 0xfff, v101
	v_mul_u32_u24_e32 v13, 0x5400, v101
	v_lshl_add_u32 v13, v11, 3, v13
	v_add_u32_e32 v13, 0x3040, v13
	v_cmp_eq_u32_e32 vcc, 0, v12
	v_add_u32_e32 v102, 0xffffac00, v13
	v_cndmask_b32_e32 v102, v102, v13, vcc
	v_cmp_eq_u32_e32 vcc, s44, v12
	v_add_u32_e32 v103, 0x5400, v13
	v_cndmask_b32_e32 v103, v103, v13, vcc
	v_lshlrev_b32_e32 v104, 4, v11
	v_add_u32_e32 v104, 0x3000, v104
	global_load_dwordx2 v[14:15], v13, s[18:19]
	global_load_dwordx2 v[16:17], v102, s[18:19]
	global_load_dwordx2 v[18:19], v103, s[18:19]
	global_load_dwordx4 v[20:23], v104, s[90:91]
	v_add_u32_e32 v100, 0x200, v2
	v_mul_u32_u24_e32 v26, 0xcccd, v100
	v_lshrrev_b32_e32 v26, 22, v26
	v_mul_u32_u24_e32 v101, 0x50, v26
	v_sub_u32_e32 v27, v100, v101
	v_add_u32_e32 v101, s52, v26
	v_and_b32_e32 v28, 0xfff, v101
	v_mul_u32_u24_e32 v29, 0x5400, v101
	v_lshl_add_u32 v29, v27, 3, v29
	v_add_u32_e32 v29, 0x3040, v29
	v_cmp_eq_u32_e32 vcc, 0, v28
	v_add_u32_e32 v102, 0xffffac00, v29
	v_cndmask_b32_e32 v102, v102, v29, vcc
	v_cmp_eq_u32_e32 vcc, s44, v28
	v_add_u32_e32 v103, 0x5400, v29
	v_cndmask_b32_e32 v103, v103, v29, vcc
	v_lshlrev_b32_e32 v104, 4, v27
	v_add_u32_e32 v104, 0x3000, v104
	global_load_dwordx2 v[30:31], v29, s[18:19]
	global_load_dwordx2 v[32:33], v102, s[18:19]
	global_load_dwordx2 v[34:35], v103, s[18:19]
	global_load_dwordx4 v[36:39], v104, s[90:91]
	v_add_u32_e32 v100, 0x400, v2
	v_mul_u32_u24_e32 v42, 0xcccd, v100
	v_lshrrev_b32_e32 v42, 22, v42
	v_mul_u32_u24_e32 v101, 0x50, v42
	v_sub_u32_e32 v43, v100, v101
	v_add_u32_e32 v101, s52, v42
	v_and_b32_e32 v44, 0xfff, v101
	v_mul_u32_u24_e32 v45, 0x5400, v101
	v_lshl_add_u32 v45, v43, 3, v45
	v_add_u32_e32 v45, 0x3040, v45
	v_cmp_eq_u32_e32 vcc, 0, v44
	v_add_u32_e32 v102, 0xffffac00, v45
	v_cndmask_b32_e32 v102, v102, v45, vcc
	v_cmp_eq_u32_e32 vcc, s44, v44
	v_add_u32_e32 v103, 0x5400, v45
	v_cndmask_b32_e32 v103, v103, v45, vcc
	v_lshlrev_b32_e32 v104, 4, v43
	v_add_u32_e32 v104, 0x3000, v104
	global_load_dwordx2 v[46:47], v45, s[18:19]
	global_load_dwordx2 v[48:49], v102, s[18:19]
	global_load_dwordx2 v[50:51], v103, s[18:19]
	global_load_dwordx4 v[52:55], v104, s[90:91]
	v_add_u32_e32 v100, 0x600, v2
	v_mul_u32_u24_e32 v58, 0xcccd, v100
	v_lshrrev_b32_e32 v58, 22, v58
	v_mul_u32_u24_e32 v101, 0x50, v58
	v_sub_u32_e32 v59, v100, v101
	v_add_u32_e32 v101, s52, v58
	v_and_b32_e32 v60, 0xfff, v101
	v_mul_u32_u24_e32 v61, 0x5400, v101
	v_lshl_add_u32 v61, v59, 3, v61
	v_add_u32_e32 v61, 0x3040, v61
	v_cmp_eq_u32_e32 vcc, 0, v60
	v_add_u32_e32 v102, 0xffffac00, v61
	v_cndmask_b32_e32 v102, v102, v61, vcc
	v_cmp_eq_u32_e32 vcc, s44, v60
	v_add_u32_e32 v103, 0x5400, v61
	v_cndmask_b32_e32 v103, v103, v61, vcc
	v_lshlrev_b32_e32 v104, 4, v59
	v_add_u32_e32 v104, 0x3000, v104
	global_load_dwordx2 v[62:63], v61, s[18:19]
	global_load_dwordx2 v[64:65], v102, s[18:19]
	global_load_dwordx2 v[66:67], v103, s[18:19]
	global_load_dwordx4 v[68:71], v104, s[90:91]
	v_add_u32_e32 v100, 0x800, v2
	v_mul_u32_u24_e32 v74, 0xcccd, v100
	v_lshrrev_b32_e32 v74, 22, v74
	v_mul_u32_u24_e32 v101, 0x50, v74
	v_sub_u32_e32 v75, v100, v101
	v_add_u32_e32 v101, s52, v74
	v_and_b32_e32 v76, 0xfff, v101
	v_mul_u32_u24_e32 v77, 0x5400, v101
	v_lshl_add_u32 v77, v75, 3, v77
	v_add_u32_e32 v77, 0x3040, v77
	v_cmp_eq_u32_e32 vcc, 0, v76
	v_add_u32_e32 v102, 0xffffac00, v77
	v_cndmask_b32_e32 v102, v102, v77, vcc
	v_cmp_eq_u32_e32 vcc, s44, v76
	v_add_u32_e32 v103, 0x5400, v77
	v_cndmask_b32_e32 v103, v103, v77, vcc
	v_lshlrev_b32_e32 v104, 4, v75
	v_add_u32_e32 v104, 0x3000, v104
	global_load_dwordx2 v[78:79], v77, s[18:19]
	global_load_dwordx2 v[80:81], v102, s[18:19]
	global_load_dwordx2 v[82:83], v103, s[18:19]
	global_load_dwordx4 v[84:87], v104, s[90:91]
	v_mov_b32_e32 v105, 0xbfb8aa3b
	v_mov_b32_e32 v106, 0x4038aa3b
	s_waitcnt vmcnt(16)
	v_cmp_eq_u32_e32 vcc, 0, v12
	v_cndmask_b32_e64 v16, v16, 0, vcc
	v_cndmask_b32_e64 v17, v17, 0, vcc
	v_cmp_eq_u32_e32 vcc, s44, v12
	v_cndmask_b32_e64 v18, v18, 0, vcc
	v_cndmask_b32_e64 v19, v19, 0, vcc
	v_cmp_gt_u32_e64 s[6:7], 32, v11
	v_add_u32_e32 v107, -32, v11
	v_cmp_gt_u32_e64 s[8:9], 16, v107
	v_cndmask_b32_e64 v108, v105, v106, s[6:7]
	v_cndmask_b32_e64 v109, 1.0, 2.0, s[6:7]
	v_lshlrev_b32_e32 v110, 16, v14
	v_lshlrev_b32_e32 v111, 16, v16
	v_lshlrev_b32_e32 v112, 16, v18
	v_add_f32_e32 v111, v111, v112
	v_fma_f32 v111, v111, 0.5, -v110
	v_fmac_f32_e32 v110, v20, v111
	v_mul_f32_e32 v113, v108, v110
	v_exp_f32_e32 v113, v113
	s_nop 0
	v_add_f32_e32 v113, 1.0, v113
	v_div_scale_f32 v114, s[0:1], v113, v113, v109
	v_rcp_f32_e32 v115, v114
	v_div_scale_f32 v116, vcc, v109, v113, v109
	v_fma_f32 v117, -v114, v115, 1.0
	v_fmac_f32_e32 v115, v117, v115
	v_mul_f32_e32 v117, v116, v115
	v_fma_f32 v118, -v114, v117, v116
	v_fmac_f32_e32 v117, v118, v115
	v_fma_f32 v114, -v114, v117, v116
	v_div_fmas_f32 v114, v114, v115, v117
	v_div_fixup_f32 v114, v114, v113, v109
	v_sub_f32_e32 v115, 1.0, v114
	v_cndmask_b32_e64 v114, v114, v115, s[6:7]
	v_cndmask_b32_e64 v120, v114, v110, s[8:9]
	v_and_b32_e32 v110, 0xffff0000, v14
	v_and_b32_e32 v111, 0xffff0000, v16
	v_and_b32_e32 v112, 0xffff0000, v18
	v_add_f32_e32 v111, v111, v112
	v_fma_f32 v111, v111, 0.5, -v110
	v_fmac_f32_e32 v110, v21, v111
	v_mul_f32_e32 v113, v108, v110
	v_exp_f32_e32 v113, v113
	s_nop 0
	v_add_f32_e32 v113, 1.0, v113
	v_div_scale_f32 v114, s[0:1], v113, v113, v109
	v_rcp_f32_e32 v115, v114
; DEVINL u16 f2bf(float a) { return (u16)(pk2(a, 0.f) & 0xffffu); }
; DEVINL float bf2f(u16 h) { return __uint_as_float(((unsigned)h) << 16); }
; DEVINL float sigm(float x) { return 1.f / (1.f + __expf(-x)); }
; DEVINL float tanh_(float x) { return 1.f - 2.f / (__expf(2.f * x) + 1.f); }
; DEVINL float rw_shift2(const char* colsb, float muv, unsigned o, int s) {
;   const unsigned op = (s > 0) ? o - (unsigned)(NCP * 2) : o;
;   const unsigned on = (s < S_ - 1) ? o + (unsigned)(NCP * 2) : o;
;   float cur = bf2f(*(const u16*)(colsb + o));
;   float prv = bf2f(*(const u16*)(colsb + op));
;   float nxt = bf2f(*(const u16*)(colsb + on));
;   if (s == 0) prv = 0.f;
;   if (s == S_ - 1) nxt = 0.f;
;   return cur + muv * (0.5f * (prv + nxt) - cur);
; }
; DEVINL void rw_prep_unit(const Params& p, int unit) {
;     ...
; #pragma unroll 5
;   for (int idx = tid; idx < 32 * 320; idx += 512) {
;     int i = idx / 320, j = idx % 320;
;     int t = tok0 + i; int s = t & (S_ - 1);
;     unsigned o = ((unsigned)t * (unsigned)NCP + (unsigned)(C_RW + 3072 + j)) * 2u;
;     float v = rw_shift2(colsb, p.rw_mu[3072 + j], o, s);
;     if (j < 128) v = tanh_(v);
;     else if (j >= 192) v = sigm(v);
;     AL[i * 328 + j] = f2bf(v);
;   }
	v_div_scale_f32 v116, vcc, v109, v113, v109
	v_fma_f32 v117, -v114, v115, 1.0
	v_fmac_f32_e32 v115, v117, v115
	v_mul_f32_e32 v117, v116, v115
	v_fma_f32 v118, -v114, v117, v116
	v_fmac_f32_e32 v117, v118, v115
	v_fma_f32 v114, -v114, v117, v116
	v_div_fmas_f32 v114, v114, v115, v117
	v_div_fixup_f32 v114, v114, v113, v109
	v_sub_f32_e32 v115, 1.0, v114
	v_cndmask_b32_e64 v114, v114, v115, s[6:7]
	v_cndmask_b32_e64 v121, v114, v110, s[8:9]
	v_lshlrev_b32_e32 v110, 16, v15
	v_lshlrev_b32_e32 v111, 16, v17
	v_lshlrev_b32_e32 v112, 16, v19
	v_add_f32_e32 v111, v111, v112
	v_fma_f32 v111, v111, 0.5, -v110
	v_fmac_f32_e32 v110, v22, v111
	v_mul_f32_e32 v113, v108, v110
	v_exp_f32_e32 v113, v113
	s_nop 0
	v_add_f32_e32 v113, 1.0, v113
	v_div_scale_f32 v114, s[0:1], v113, v113, v109
	v_rcp_f32_e32 v115, v114
	v_div_scale_f32 v116, vcc, v109, v113, v109
	v_fma_f32 v117, -v114, v115, 1.0
	v_fmac_f32_e32 v115, v117, v115
	v_mul_f32_e32 v117, v116, v115
	v_fma_f32 v118, -v114, v117, v116
	v_fmac_f32_e32 v117, v118, v115
	v_fma_f32 v114, -v114, v117, v116
	v_div_fmas_f32 v114, v114, v115, v117
	v_div_fixup_f32 v114, v114, v113, v109
	v_sub_f32_e32 v115, 1.0, v114
	v_cndmask_b32_e64 v114, v114, v115, s[6:7]
	v_cndmask_b32_e64 v122, v114, v110, s[8:9]
	v_and_b32_e32 v110, 0xffff0000, v15
	v_and_b32_e32 v111, 0xffff0000, v17
	v_and_b32_e32 v112, 0xffff0000, v19
	v_add_f32_e32 v111, v111, v112
	v_fma_f32 v111, v111, 0.5, -v110
	v_fmac_f32_e32 v110, v23, v111
	v_mul_f32_e32 v113, v108, v110
	v_exp_f32_e32 v113, v113
	s_nop 0
	v_add_f32_e32 v113, 1.0, v113
	v_div_scale_f32 v114, s[0:1], v113, v113, v109
	v_rcp_f32_e32 v115, v114
	v_div_scale_f32 v116, vcc, v109, v113, v109
	v_fma_f32 v117, -v114, v115, 1.0
	v_fmac_f32_e32 v115, v117, v115
	v_mul_f32_e32 v117, v116, v115
	v_fma_f32 v118, -v114, v117, v116
	v_fmac_f32_e32 v117, v118, v115
	v_fma_f32 v114, -v114, v117, v116
	v_div_fmas_f32 v114, v114, v115, v117
	v_div_fixup_f32 v114, v114, v113, v109
	v_sub_f32_e32 v115, 1.0, v114
	v_cndmask_b32_e64 v114, v114, v115, s[6:7]
	v_cndmask_b32_e64 v123, v114, v110, s[8:9]
	v_cvt_pk_bf16_f32 v124, v120, v121
	v_cvt_pk_bf16_f32 v125, v122, v123
	v_mul_u32_u24_e32 v126, 0x290, v10
	v_lshl_add_u32 v126, v11, 3, v126
	ds_write_b64 v126, v[124:125] offset:16
	s_waitcnt vmcnt(12)
	v_cmp_eq_u32_e32 vcc, 0, v28
	v_cndmask_b32_e64 v32, v32, 0, vcc
	v_cndmask_b32_e64 v33, v33, 0, vcc
	v_cmp_eq_u32_e32 vcc, s44, v28
	v_cndmask_b32_e64 v34, v34, 0, vcc
	v_cndmask_b32_e64 v35, v35, 0, vcc
	v_cmp_gt_u32_e64 s[6:7], 32, v27
	v_add_u32_e32 v107, -32, v27
	v_cmp_gt_u32_e64 s[8:9], 16, v107
	v_cndmask_b32_e64 v108, v105, v106, s[6:7]
	v_cndmask_b32_e64 v109, 1.0, 2.0, s[6:7]
	v_lshlrev_b32_e32 v110, 16, v30
	v_lshlrev_b32_e32 v111, 16, v32
	v_lshlrev_b32_e32 v112, 16, v34
	v_add_f32_e32 v111, v111, v112
	v_fma_f32 v111, v111, 0.5, -v110
	v_fmac_f32_e32 v110, v36, v111
	v_mul_f32_e32 v113, v108, v110
	v_exp_f32_e32 v113, v113
	s_nop 0
	v_add_f32_e32 v113, 1.0, v113
	v_div_scale_f32 v114, s[0:1], v113, v113, v109
	v_rcp_f32_e32 v115, v114
	v_div_scale_f32 v116, vcc, v109, v113, v109
	v_fma_f32 v117, -v114, v115, 1.0
	v_fmac_f32_e32 v115, v117, v115
	v_mul_f32_e32 v117, v116, v115
	v_fma_f32 v118, -v114, v117, v116
	v_fmac_f32_e32 v117, v118, v115
	v_fma_f32 v114, -v114, v117, v116
	v_div_fmas_f32 v114, v114, v115, v117
	v_div_fixup_f32 v114, v114, v113, v109
	v_sub_f32_e32 v115, 1.0, v114
	v_cndmask_b32_e64 v114, v114, v115, s[6:7]
	v_cndmask_b32_e64 v120, v114, v110, s[8:9]
	v_and_b32_e32 v110, 0xffff0000, v30
	v_and_b32_e32 v111, 0xffff0000, v32
	v_and_b32_e32 v112, 0xffff0000, v34
	v_add_f32_e32 v111, v111, v112
	v_fma_f32 v111, v111, 0.5, -v110
	v_fmac_f32_e32 v110, v37, v111
	v_mul_f32_e32 v113, v108, v110
	v_exp_f32_e32 v113, v113
	s_nop 0
	v_add_f32_e32 v113, 1.0, v113
	v_div_scale_f32 v114, s[0:1], v113, v113, v109
	v_rcp_f32_e32 v115, v114
	v_div_scale_f32 v116, vcc, v109, v113, v109
	v_fma_f32 v117, -v114, v115, 1.0
	v_fmac_f32_e32 v115, v117, v115
	v_mul_f32_e32 v117, v116, v115
	v_fma_f32 v118, -v114, v117, v116
	v_fmac_f32_e32 v117, v118, v115
	v_fma_f32 v114, -v114, v117, v116
	v_div_fmas_f32 v114, v114, v115, v117
	v_div_fixup_f32 v114, v114, v113, v109
	v_sub_f32_e32 v115, 1.0, v114
	v_cndmask_b32_e64 v114, v114, v115, s[6:7]
	v_cndmask_b32_e64 v121, v114, v110, s[8:9]
	v_lshlrev_b32_e32 v110, 16, v31
	v_lshlrev_b32_e32 v111, 16, v33
	v_lshlrev_b32_e32 v112, 16, v35
	v_add_f32_e32 v111, v111, v112
	v_fma_f32 v111, v111, 0.5, -v110
	v_fmac_f32_e32 v110, v38, v111
	v_mul_f32_e32 v113, v108, v110
	v_exp_f32_e32 v113, v113
	s_nop 0
	v_add_f32_e32 v113, 1.0, v113
	v_div_scale_f32 v114, s[0:1], v113, v113, v109
	v_rcp_f32_e32 v115, v114
	v_div_scale_f32 v116, vcc, v109, v113, v109
	v_fma_f32 v117, -v114, v115, 1.0
	v_fmac_f32_e32 v115, v117, v115
	v_mul_f32_e32 v117, v116, v115
	v_fma_f32 v118, -v114, v117, v116
	v_fmac_f32_e32 v117, v118, v115
	v_fma_f32 v114, -v114, v117, v116
	v_div_fmas_f32 v114, v114, v115, v117
	v_div_fixup_f32 v114, v114, v113, v109
	v_sub_f32_e32 v115, 1.0, v114
	v_cndmask_b32_e64 v114, v114, v115, s[6:7]
	v_cndmask_b32_e64 v122, v114, v110, s[8:9]
	v_and_b32_e32 v110, 0xffff0000, v31
	v_and_b32_e32 v111, 0xffff0000, v33
	v_and_b32_e32 v112, 0xffff0000, v35
	v_add_f32_e32 v111, v111, v112
	v_fma_f32 v111, v111, 0.5, -v110
	v_fmac_f32_e32 v110, v39, v111
	v_mul_f32_e32 v113, v108, v110
	v_exp_f32_e32 v113, v113
	s_nop 0
	v_add_f32_e32 v113, 1.0, v113
	v_div_scale_f32 v114, s[0:1], v113, v113, v109
	v_rcp_f32_e32 v115, v114
	v_div_scale_f32 v116, vcc, v109, v113, v109
	v_fma_f32 v117, -v114, v115, 1.0
	v_fmac_f32_e32 v115, v117, v115
	v_mul_f32_e32 v117, v116, v115
	v_fma_f32 v118, -v114, v117, v116
	v_fmac_f32_e32 v117, v118, v115
	v_fma_f32 v114, -v114, v117, v116
	v_div_fmas_f32 v114, v114, v115, v117
	v_div_fixup_f32 v114, v114, v113, v109
	v_sub_f32_e32 v115, 1.0, v114
	v_cndmask_b32_e64 v114, v114, v115, s[6:7]
	v_cndmask_b32_e64 v123, v114, v110, s[8:9]
	v_cvt_pk_bf16_f32 v124, v120, v121
	v_cvt_pk_bf16_f32 v125, v122, v123
	v_mul_u32_u24_e32 v126, 0x290, v26
	v_lshl_add_u32 v126, v27, 3, v126
	ds_write_b64 v126, v[124:125] offset:16
	s_waitcnt vmcnt(8)
; DEVINL u16 f2bf(float a) { return (u16)(pk2(a, 0.f) & 0xffffu); }
; DEVINL float bf2f(u16 h) { return __uint_as_float(((unsigned)h) << 16); }
; DEVINL float sigm(float x) { return 1.f / (1.f + __expf(-x)); }
; DEVINL float tanh_(float x) { return 1.f - 2.f / (__expf(2.f * x) + 1.f); }
; DEVINL float rw_shift2(const char* colsb, float muv, unsigned o, int s) {
;   const unsigned op = (s > 0) ? o - (unsigned)(NCP * 2) : o;
;   const unsigned on = (s < S_ - 1) ? o + (unsigned)(NCP * 2) : o;
;   float cur = bf2f(*(const u16*)(colsb + o));
;   float prv = bf2f(*(const u16*)(colsb + op));
;   float nxt = bf2f(*(const u16*)(colsb + on));
;   if (s == 0) prv = 0.f;
;   if (s == S_ - 1) nxt = 0.f;
;   return cur + muv * (0.5f * (prv + nxt) - cur);
; }
; DEVINL void rw_prep_unit(const Params& p, int unit) {
;     ...
; #pragma unroll 5
;   for (int idx = tid; idx < 32 * 320; idx += 512) {
;     int i = idx / 320, j = idx % 320;
;     int t = tok0 + i; int s = t & (S_ - 1);
;     unsigned o = ((unsigned)t * (unsigned)NCP + (unsigned)(C_RW + 3072 + j)) * 2u;
;     float v = rw_shift2(colsb, p.rw_mu[3072 + j], o, s);
;     if (j < 128) v = tanh_(v);
;     else if (j >= 192) v = sigm(v);
;     AL[i * 328 + j] = f2bf(v);
;   }
	v_cmp_eq_u32_e32 vcc, 0, v44
	v_cndmask_b32_e64 v48, v48, 0, vcc
	v_cndmask_b32_e64 v49, v49, 0, vcc
	v_cmp_eq_u32_e32 vcc, s44, v44
	v_cndmask_b32_e64 v50, v50, 0, vcc
	v_cndmask_b32_e64 v51, v51, 0, vcc
	v_cmp_gt_u32_e64 s[6:7], 32, v43
	v_add_u32_e32 v107, -32, v43
	v_cmp_gt_u32_e64 s[8:9], 16, v107
	v_cndmask_b32_e64 v108, v105, v106, s[6:7]
	v_cndmask_b32_e64 v109, 1.0, 2.0, s[6:7]
	v_lshlrev_b32_e32 v110, 16, v46
	v_lshlrev_b32_e32 v111, 16, v48
	v_lshlrev_b32_e32 v112, 16, v50
	v_add_f32_e32 v111, v111, v112
	v_fma_f32 v111, v111, 0.5, -v110
	v_fmac_f32_e32 v110, v52, v111
	v_mul_f32_e32 v113, v108, v110
	v_exp_f32_e32 v113, v113
	s_nop 0
	v_add_f32_e32 v113, 1.0, v113
	v_div_scale_f32 v114, s[0:1], v113, v113, v109
	v_rcp_f32_e32 v115, v114
	v_div_scale_f32 v116, vcc, v109, v113, v109
	v_fma_f32 v117, -v114, v115, 1.0
	v_fmac_f32_e32 v115, v117, v115
	v_mul_f32_e32 v117, v116, v115
	v_fma_f32 v118, -v114, v117, v116
	v_fmac_f32_e32 v117, v118, v115
	v_fma_f32 v114, -v114, v117, v116
	v_div_fmas_f32 v114, v114, v115, v117
	v_div_fixup_f32 v114, v114, v113, v109
	v_sub_f32_e32 v115, 1.0, v114
	v_cndmask_b32_e64 v114, v114, v115, s[6:7]
	v_cndmask_b32_e64 v120, v114, v110, s[8:9]
	v_and_b32_e32 v110, 0xffff0000, v46
	v_and_b32_e32 v111, 0xffff0000, v48
	v_and_b32_e32 v112, 0xffff0000, v50
	v_add_f32_e32 v111, v111, v112
	v_fma_f32 v111, v111, 0.5, -v110
	v_fmac_f32_e32 v110, v53, v111
	v_mul_f32_e32 v113, v108, v110
	v_exp_f32_e32 v113, v113
	s_nop 0
	v_add_f32_e32 v113, 1.0, v113
	v_div_scale_f32 v114, s[0:1], v113, v113, v109
	v_rcp_f32_e32 v115, v114
	v_div_scale_f32 v116, vcc, v109, v113, v109
	v_fma_f32 v117, -v114, v115, 1.0
	v_fmac_f32_e32 v115, v117, v115
	v_mul_f32_e32 v117, v116, v115
	v_fma_f32 v118, -v114, v117, v116
	v_fmac_f32_e32 v117, v118, v115
	v_fma_f32 v114, -v114, v117, v116
	v_div_fmas_f32 v114, v114, v115, v117
	v_div_fixup_f32 v114, v114, v113, v109
	v_sub_f32_e32 v115, 1.0, v114
	v_cndmask_b32_e64 v114, v114, v115, s[6:7]
	v_cndmask_b32_e64 v121, v114, v110, s[8:9]
	v_lshlrev_b32_e32 v110, 16, v47
	v_lshlrev_b32_e32 v111, 16, v49
	v_lshlrev_b32_e32 v112, 16, v51
	v_add_f32_e32 v111, v111, v112
	v_fma_f32 v111, v111, 0.5, -v110
	v_fmac_f32_e32 v110, v54, v111
	v_mul_f32_e32 v113, v108, v110
	v_exp_f32_e32 v113, v113
	s_nop 0
	v_add_f32_e32 v113, 1.0, v113
	v_div_scale_f32 v114, s[0:1], v113, v113, v109
	v_rcp_f32_e32 v115, v114
	v_div_scale_f32 v116, vcc, v109, v113, v109
	v_fma_f32 v117, -v114, v115, 1.0
	v_fmac_f32_e32 v115, v117, v115
	v_mul_f32_e32 v117, v116, v115
	v_fma_f32 v118, -v114, v117, v116
	v_fmac_f32_e32 v117, v118, v115
	v_fma_f32 v114, -v114, v117, v116
	v_div_fmas_f32 v114, v114, v115, v117
	v_div_fixup_f32 v114, v114, v113, v109
	v_sub_f32_e32 v115, 1.0, v114
	v_cndmask_b32_e64 v114, v114, v115, s[6:7]
	v_cndmask_b32_e64 v122, v114, v110, s[8:9]
	v_and_b32_e32 v110, 0xffff0000, v47
	v_and_b32_e32 v111, 0xffff0000, v49
	v_and_b32_e32 v112, 0xffff0000, v51
	v_add_f32_e32 v111, v111, v112
	v_fma_f32 v111, v111, 0.5, -v110
	v_fmac_f32_e32 v110, v55, v111
	v_mul_f32_e32 v113, v108, v110
	v_exp_f32_e32 v113, v113
	s_nop 0
	v_add_f32_e32 v113, 1.0, v113
	v_div_scale_f32 v114, s[0:1], v113, v113, v109
	v_rcp_f32_e32 v115, v114
	v_div_scale_f32 v116, vcc, v109, v113, v109
	v_fma_f32 v117, -v114, v115, 1.0
	v_fmac_f32_e32 v115, v117, v115
	v_mul_f32_e32 v117, v116, v115
	v_fma_f32 v118, -v114, v117, v116
	v_fmac_f32_e32 v117, v118, v115
	v_fma_f32 v114, -v114, v117, v116
	v_div_fmas_f32 v114, v114, v115, v117
	v_div_fixup_f32 v114, v114, v113, v109
	v_sub_f32_e32 v115, 1.0, v114
	v_cndmask_b32_e64 v114, v114, v115, s[6:7]
	v_cndmask_b32_e64 v123, v114, v110, s[8:9]
	v_cvt_pk_bf16_f32 v124, v120, v121
	v_cvt_pk_bf16_f32 v125, v122, v123
	v_mul_u32_u24_e32 v126, 0x290, v42
	v_lshl_add_u32 v126, v43, 3, v126
	ds_write_b64 v126, v[124:125] offset:16
	s_waitcnt vmcnt(4)
	v_cmp_eq_u32_e32 vcc, 0, v60
	v_cndmask_b32_e64 v64, v64, 0, vcc
	v_cndmask_b32_e64 v65, v65, 0, vcc
	v_cmp_eq_u32_e32 vcc, s44, v60
	v_cndmask_b32_e64 v66, v66, 0, vcc
	v_cndmask_b32_e64 v67, v67, 0, vcc
	v_cmp_gt_u32_e64 s[6:7], 32, v59
	v_add_u32_e32 v107, -32, v59
	v_cmp_gt_u32_e64 s[8:9], 16, v107
	v_cndmask_b32_e64 v108, v105, v106, s[6:7]
	v_cndmask_b32_e64 v109, 1.0, 2.0, s[6:7]
	v_lshlrev_b32_e32 v110, 16, v62
	v_lshlrev_b32_e32 v111, 16, v64
	v_lshlrev_b32_e32 v112, 16, v66
	v_add_f32_e32 v111, v111, v112
	v_fma_f32 v111, v111, 0.5, -v110
	v_fmac_f32_e32 v110, v68, v111
	v_mul_f32_e32 v113, v108, v110
	v_exp_f32_e32 v113, v113
	s_nop 0
	v_add_f32_e32 v113, 1.0, v113
	v_div_scale_f32 v114, s[0:1], v113, v113, v109
	v_rcp_f32_e32 v115, v114
	v_div_scale_f32 v116, vcc, v109, v113, v109
	v_fma_f32 v117, -v114, v115, 1.0
	v_fmac_f32_e32 v115, v117, v115
	v_mul_f32_e32 v117, v116, v115
	v_fma_f32 v118, -v114, v117, v116
	v_fmac_f32_e32 v117, v118, v115
	v_fma_f32 v114, -v114, v117, v116
	v_div_fmas_f32 v114, v114, v115, v117
	v_div_fixup_f32 v114, v114, v113, v109
	v_sub_f32_e32 v115, 1.0, v114
	v_cndmask_b32_e64 v114, v114, v115, s[6:7]
	v_cndmask_b32_e64 v120, v114, v110, s[8:9]
	v_and_b32_e32 v110, 0xffff0000, v62
	v_and_b32_e32 v111, 0xffff0000, v64
	v_and_b32_e32 v112, 0xffff0000, v66
	v_add_f32_e32 v111, v111, v112
	v_fma_f32 v111, v111, 0.5, -v110
	v_fmac_f32_e32 v110, v69, v111
	v_mul_f32_e32 v113, v108, v110
	v_exp_f32_e32 v113, v113
	s_nop 0
	v_add_f32_e32 v113, 1.0, v113
	v_div_scale_f32 v114, s[0:1], v113, v113, v109
	v_rcp_f32_e32 v115, v114
	v_div_scale_f32 v116, vcc, v109, v113, v109
	v_fma_f32 v117, -v114, v115, 1.0
	v_fmac_f32_e32 v115, v117, v115
	v_mul_f32_e32 v117, v116, v115
	v_fma_f32 v118, -v114, v117, v116
; DEVINL u16 f2bf(float a) { return (u16)(pk2(a, 0.f) & 0xffffu); }
; DEVINL float sigm(float x) { return 1.f / (1.f + __expf(-x)); }
; DEVINL float tanh_(float x) { return 1.f - 2.f / (__expf(2.f * x) + 1.f); }
; DEVINL void rw_prep_unit(const Params& p, int unit) {
;     ...
; #pragma unroll 5
;   for (int idx = tid; idx < 32 * 320; idx += 512) {
;     int i = idx / 320, j = idx % 320;
;     int t = tok0 + i; int s = t & (S_ - 1);
;     unsigned o = ((unsigned)t * (unsigned)NCP + (unsigned)(C_RW + 3072 + j)) * 2u;
;     float v = rw_shift2(colsb, p.rw_mu[3072 + j], o, s);
;     if (j < 128) v = tanh_(v);
;     else if (j >= 192) v = sigm(v);
;     AL[i * 328 + j] = f2bf(v);
;   }
;   __syncthreads();
;     ...
;       f32x4 awf[4], awb[4], aa[4], ag[4];
; #pragma unroll
;       for (int n = 0; n < 4; ++n) { awf[n] = f32x4{0, 0, 0, 0}; awb[n] = awf[n]; aa[n] = awf[n]; ag[n] = awf[n]; }
;       const u16* arow = AL + (mt * 16 + l15) * 328 + 8 * g;
	v_fmac_f32_e32 v117, v118, v115
	v_fma_f32 v114, -v114, v117, v116
	v_div_fmas_f32 v114, v114, v115, v117
	v_div_fixup_f32 v114, v114, v113, v109
	v_sub_f32_e32 v115, 1.0, v114
	v_cndmask_b32_e64 v114, v114, v115, s[6:7]
	v_cndmask_b32_e64 v121, v114, v110, s[8:9]
	v_lshlrev_b32_e32 v110, 16, v63
	v_lshlrev_b32_e32 v111, 16, v65
	v_lshlrev_b32_e32 v112, 16, v67
	v_add_f32_e32 v111, v111, v112
	v_fma_f32 v111, v111, 0.5, -v110
	v_fmac_f32_e32 v110, v70, v111
	v_mul_f32_e32 v113, v108, v110
	v_exp_f32_e32 v113, v113
	s_nop 0
	v_add_f32_e32 v113, 1.0, v113
	v_div_scale_f32 v114, s[0:1], v113, v113, v109
	v_rcp_f32_e32 v115, v114
	v_div_scale_f32 v116, vcc, v109, v113, v109
	v_fma_f32 v117, -v114, v115, 1.0
	v_fmac_f32_e32 v115, v117, v115
	v_mul_f32_e32 v117, v116, v115
	v_fma_f32 v118, -v114, v117, v116
	v_fmac_f32_e32 v117, v118, v115
	v_fma_f32 v114, -v114, v117, v116
	v_div_fmas_f32 v114, v114, v115, v117
	v_div_fixup_f32 v114, v114, v113, v109
	v_sub_f32_e32 v115, 1.0, v114
	v_cndmask_b32_e64 v114, v114, v115, s[6:7]
	v_cndmask_b32_e64 v122, v114, v110, s[8:9]
	v_and_b32_e32 v110, 0xffff0000, v63
	v_and_b32_e32 v111, 0xffff0000, v65
	v_and_b32_e32 v112, 0xffff0000, v67
	v_add_f32_e32 v111, v111, v112
	v_fma_f32 v111, v111, 0.5, -v110
	v_fmac_f32_e32 v110, v71, v111
	v_mul_f32_e32 v113, v108, v110
	v_exp_f32_e32 v113, v113
	s_nop 0
	v_add_f32_e32 v113, 1.0, v113
	v_div_scale_f32 v114, s[0:1], v113, v113, v109
	v_rcp_f32_e32 v115, v114
	v_div_scale_f32 v116, vcc, v109, v113, v109
	v_fma_f32 v117, -v114, v115, 1.0
	v_fmac_f32_e32 v115, v117, v115
	v_mul_f32_e32 v117, v116, v115
	v_fma_f32 v118, -v114, v117, v116
	v_fmac_f32_e32 v117, v118, v115
	v_fma_f32 v114, -v114, v117, v116
	v_div_fmas_f32 v114, v114, v115, v117
	v_div_fixup_f32 v114, v114, v113, v109
	v_sub_f32_e32 v115, 1.0, v114
	v_cndmask_b32_e64 v114, v114, v115, s[6:7]
	v_cndmask_b32_e64 v123, v114, v110, s[8:9]
	v_cvt_pk_bf16_f32 v124, v120, v121
	v_cvt_pk_bf16_f32 v125, v122, v123
	v_mul_u32_u24_e32 v126, 0x290, v58
	v_lshl_add_u32 v126, v59, 3, v126
	ds_write_b64 v126, v[124:125] offset:16
	s_waitcnt vmcnt(0)
	v_cmp_eq_u32_e32 vcc, 0, v76
	v_cndmask_b32_e64 v80, v80, 0, vcc
	v_cndmask_b32_e64 v81, v81, 0, vcc
	v_cmp_eq_u32_e32 vcc, s44, v76
	v_cndmask_b32_e64 v82, v82, 0, vcc
	v_cndmask_b32_e64 v83, v83, 0, vcc
	v_cmp_gt_u32_e64 s[6:7], 32, v75
	v_add_u32_e32 v107, -32, v75
	v_cmp_gt_u32_e64 s[8:9], 16, v107
	v_cndmask_b32_e64 v108, v105, v106, s[6:7]
	v_cndmask_b32_e64 v109, 1.0, 2.0, s[6:7]
	v_lshlrev_b32_e32 v110, 16, v78
	v_lshlrev_b32_e32 v111, 16, v80
	v_lshlrev_b32_e32 v112, 16, v82
	v_add_f32_e32 v111, v111, v112
	v_fma_f32 v111, v111, 0.5, -v110
	v_fmac_f32_e32 v110, v84, v111
	v_mul_f32_e32 v113, v108, v110
	v_exp_f32_e32 v113, v113
	s_nop 0
	v_add_f32_e32 v113, 1.0, v113
	v_div_scale_f32 v114, s[0:1], v113, v113, v109
	v_rcp_f32_e32 v115, v114
	v_div_scale_f32 v116, vcc, v109, v113, v109
	v_fma_f32 v117, -v114, v115, 1.0
	v_fmac_f32_e32 v115, v117, v115
	v_mul_f32_e32 v117, v116, v115
	v_fma_f32 v118, -v114, v117, v116
	v_fmac_f32_e32 v117, v118, v115
	v_fma_f32 v114, -v114, v117, v116
	v_div_fmas_f32 v114, v114, v115, v117
	v_div_fixup_f32 v114, v114, v113, v109
	v_sub_f32_e32 v115, 1.0, v114
	v_cndmask_b32_e64 v114, v114, v115, s[6:7]
	v_cndmask_b32_e64 v120, v114, v110, s[8:9]
	v_and_b32_e32 v110, 0xffff0000, v78
	v_and_b32_e32 v111, 0xffff0000, v80
	v_and_b32_e32 v112, 0xffff0000, v82
	v_add_f32_e32 v111, v111, v112
	v_fma_f32 v111, v111, 0.5, -v110
	v_fmac_f32_e32 v110, v85, v111
	v_mul_f32_e32 v113, v108, v110
	v_exp_f32_e32 v113, v113
	s_nop 0
	v_add_f32_e32 v113, 1.0, v113
	v_div_scale_f32 v114, s[0:1], v113, v113, v109
	v_rcp_f32_e32 v115, v114
	v_div_scale_f32 v116, vcc, v109, v113, v109
	v_fma_f32 v117, -v114, v115, 1.0
	v_fmac_f32_e32 v115, v117, v115
	v_mul_f32_e32 v117, v116, v115
	v_fma_f32 v118, -v114, v117, v116
	v_fmac_f32_e32 v117, v118, v115
	v_fma_f32 v114, -v114, v117, v116
	v_div_fmas_f32 v114, v114, v115, v117
	v_div_fixup_f32 v114, v114, v113, v109
	v_sub_f32_e32 v115, 1.0, v114
	v_cndmask_b32_e64 v114, v114, v115, s[6:7]
	v_cndmask_b32_e64 v121, v114, v110, s[8:9]
	v_lshlrev_b32_e32 v110, 16, v79
	v_lshlrev_b32_e32 v111, 16, v81
	v_lshlrev_b32_e32 v112, 16, v83
	v_add_f32_e32 v111, v111, v112
	v_fma_f32 v111, v111, 0.5, -v110
	v_fmac_f32_e32 v110, v86, v111
	v_mul_f32_e32 v113, v108, v110
	v_exp_f32_e32 v113, v113
	s_nop 0
	v_add_f32_e32 v113, 1.0, v113
	v_div_scale_f32 v114, s[0:1], v113, v113, v109
	v_rcp_f32_e32 v115, v114
	v_div_scale_f32 v116, vcc, v109, v113, v109
	v_fma_f32 v117, -v114, v115, 1.0
	v_fmac_f32_e32 v115, v117, v115
	v_mul_f32_e32 v117, v116, v115
	v_fma_f32 v118, -v114, v117, v116
	v_fmac_f32_e32 v117, v118, v115
	v_fma_f32 v114, -v114, v117, v116
	v_div_fmas_f32 v114, v114, v115, v117
	v_div_fixup_f32 v114, v114, v113, v109
	v_sub_f32_e32 v115, 1.0, v114
	v_cndmask_b32_e64 v114, v114, v115, s[6:7]
	v_cndmask_b32_e64 v122, v114, v110, s[8:9]
	v_and_b32_e32 v110, 0xffff0000, v79
	v_and_b32_e32 v111, 0xffff0000, v81
	v_and_b32_e32 v112, 0xffff0000, v83
	v_add_f32_e32 v111, v111, v112
	v_fma_f32 v111, v111, 0.5, -v110
	v_fmac_f32_e32 v110, v87, v111
	v_mul_f32_e32 v113, v108, v110
	v_exp_f32_e32 v113, v113
	s_nop 0
	v_add_f32_e32 v113, 1.0, v113
	v_div_scale_f32 v114, s[0:1], v113, v113, v109
	v_rcp_f32_e32 v115, v114
	v_div_scale_f32 v116, vcc, v109, v113, v109
	v_fma_f32 v117, -v114, v115, 1.0
	v_fmac_f32_e32 v115, v117, v115
	v_mul_f32_e32 v117, v116, v115
	v_fma_f32 v118, -v114, v117, v116
	v_fmac_f32_e32 v117, v118, v115
	v_fma_f32 v114, -v114, v117, v116
	v_div_fmas_f32 v114, v114, v115, v117
	v_div_fixup_f32 v114, v114, v113, v109
	v_sub_f32_e32 v115, 1.0, v114
	v_cndmask_b32_e64 v114, v114, v115, s[6:7]
	v_cndmask_b32_e64 v123, v114, v110, s[8:9]
	v_cvt_pk_bf16_f32 v124, v120, v121
	v_cvt_pk_bf16_f32 v125, v122, v123
	v_mul_u32_u24_e32 v126, 0x290, v74
	v_lshl_add_u32 v126, v75, 3, v126
	ds_write_b64 v126, v[124:125] offset:16
	v_bfe_u32 v0, v2, 4, 2
	v_and_b32_e32 v180, 15, v2
	v_ashrrev_i32_e32 v1, 5, v2
	v_lshlrev_b32_e32 v182, 4, v0
	v_and_b32_e32 v181, -2, v1
	v_add_u32_e32 v183, 16, v182
	v_lshlrev_b32_e32 v184, 2, v180
	v_lshl_or_b32 v185, v0, 2, s52
	v_lshlrev_b32_e32 v186, 4, v180
	v_or_b32_e32 v187, 64, v182
	v_or_b32_e32 v188, 0x80, v182
	v_or_b32_e32 v190, 0xc0, v182
	s_mov_b32 s6, 0
	s_mov_b64 s[0:1], -1
	s_waitcnt lgkmcnt(0)
	s_barrier

; #define MFMA16(a, b, c) __builtin_amdgcn_mfma_f32_16x16x32_bf16(a, b, c, 0, 0, 0)
; DEVINL void rw_prep_unit(const Params& p, int unit) {
;     ...
; #pragma unroll 1
;   for (int hh = 0; hh < 2; ++hh) {
;     const int head = wave * 2 + hh;
; #pragma unroll 1
;     for (int mt = 0; mt < 2; ++mt) {
;       f32x4 awf[4], awb[4], aa[4], ag[4];
; #pragma unroll
;       for (int n = 0; n < 4; ++n) { awf[n] = f32x4{0, 0, 0, 0}; awb[n] = awf[n]; aa[n] = awf[n]; ag[n] = awf[n]; }
;       const u16* arow = AL + (mt * 16 + l15) * 328 + 8 * g;
; #pragma unroll
;       for (int ks = 0; ks < 2; ++ks) {
;         bf16x8 fwf = *(const bf16x8*)(arow + 32 * ks);
;         bf16x8 fwb = *(const bf16x8*)(arow + 64 + 32 * ks);
;         bf16x8 fa = *(const bf16x8*)(arow + 128 + 32 * ks);
; #pragma unroll
;         for (int n = 0; n < 4; ++n) {
;           const unsigned bo = (unsigned)((head * 64 + l15 * 4 + n) * 64 + 32 * ks + 8 * g) * 2u;
;           bf16x8 b1 = *(const bf16x8*)((const char*)LWF + bo);
;           bf16x8 b2 = *(const bf16x8*)((const char*)LWB + bo);
;           bf16x8 b3 = *(const bf16x8*)((const char*)LA + bo);
;           awf[n] = MFMA16(fwf, b1, awf[n]);
;           awb[n] = MFMA16(fwb, b2, awb[n]);
;           aa[n] = MFMA16(fa, b3, aa[n]);
;         }
;         __builtin_amdgcn_sched_barrier(0);
;       }
; #pragma unroll
;       for (int ks = 0; ks < 4; ++ks) {
;         bf16x8 fg = *(const bf16x8*)(arow + 192 + 32 * ks);
; #pragma unroll
;         for (int n = 0; n < 4; ++n) {
;           const unsigned bo = (unsigned)((head * 64 + l15 * 4 + n) * 128 + 32 * ks + 8 * g) * 2u;
;           bf16x8 b4 = *(const bf16x8*)((const char*)LG + bo);
;           ag[n] = MFMA16(fg, b4, ag[n]);
;         }
;         __builtin_amdgcn_sched_barrier(0);
;       }
.LBB0_382:
	global_load_dwordx4 v[0:3], v[98:99], off
	global_load_dwordx4 v[4:7], v[100:101], off
	global_load_dwordx4 v[8:11], v[102:103], off
	global_load_dwordx4 v[12:15], v[104:105], off
	global_load_dwordx4 v[16:19], v[106:107], off
	global_load_dwordx4 v[20:23], v[108:109], off
	global_load_dwordx4 v[24:27], v[110:111], off
	global_load_dwordx4 v[28:31], v[112:113], off
	global_load_dwordx4 v[32:35], v[114:115], off
	global_load_dwordx4 v[36:39], v[116:117], off
	global_load_dwordx4 v[40:43], v[118:119], off
	global_load_dwordx4 v[44:47], v[120:121], off
	global_load_dwordx4 v[64:67], v[122:123], off
	global_load_dwordx4 v[68:71], v[124:125], off
	global_load_dwordx4 v[72:75], v[126:127], off
	global_load_dwordx4 v[76:79], v[128:129], off
	global_load_dwordx4 v[80:83], v[130:131], off
	global_load_dwordx4 v[84:87], v[132:133], off
	global_load_dwordx4 v[88:91], v[134:135], off
	global_load_dwordx4 v[92:95], v[136:137], off
	global_load_dwordx4 v[194:197], v[138:139], off
	global_load_dwordx4 v[198:201], v[140:141], off
	global_load_dwordx4 v[202:205], v[142:143], off
	global_load_dwordx4 v[206:209], v[144:145], off
	global_load_dwordx4 v[48:51], v[146:147], off
	global_load_dwordx4 v[52:55], v[148:149], off
	global_load_dwordx4 v[56:59], v[150:151], off
	global_load_dwordx4 v[60:63], v[152:153], off
	global_load_dwordx4 v[210:213], v[154:155], off
	global_load_dwordx4 v[214:217], v[156:157], off
	global_load_dwordx4 v[218:221], v[158:159], off
	global_load_dwordx4 v[222:225], v[160:161], off
	global_load_dwordx4 v[226:229], v[162:163], off
	v_or_b32_e32 v96, s6, v180
	s_movk_i32 s7, 0x290
	v_mad_u32_u24 v178, v96, s7, v183
	s_xor_b64 s[82:83], s[0:1], -1
	ds_read_b128 v[230:233], v178
	ds_read_b128 v[234:237], v178 offset:128
	ds_read_b128 v[238:241], v178 offset:256
	ds_read_b128 v[242:245], v178 offset:64
	ds_read_b128 v[246:249], v178 offset:192
	ds_read_b128 v[250:253], v178 offset:320
	s_waitcnt vmcnt(21) lgkmcnt(3)
	v_mfma_f32_16x16x32_bf16 v[0:3], v[230:233], v[0:3], 0
	s_waitcnt lgkmcnt(3)
	v_mfma_f32_16x16x32_bf16 v[4:7], v[234:237], v[4:7], 0
	v_mfma_f32_16x16x32_bf16 v[8:11], v[238:241], v[8:11], 0
	v_mfma_f32_16x16x32_bf16 v[12:15], v[230:233], v[12:15], 0
	v_mfma_f32_16x16x32_bf16 v[16:19], v[234:237], v[16:19], 0
	v_mfma_f32_16x16x32_bf16 v[20:23], v[238:241], v[20:23], 0
	v_mfma_f32_16x16x32_bf16 v[24:27], v[230:233], v[24:27], 0
	v_mfma_f32_16x16x32_bf16 v[28:31], v[234:237], v[28:31], 0
	v_mfma_f32_16x16x32_bf16 v[32:35], v[238:241], v[32:35], 0
	v_mfma_f32_16x16x32_bf16 v[36:39], v[230:233], v[36:39], 0
	v_mfma_f32_16x16x32_bf16 v[40:43], v[234:237], v[40:43], 0
	v_mfma_f32_16x16x32_bf16 v[44:47], v[238:241], v[44:47], 0
	s_waitcnt vmcnt(9) lgkmcnt(0)
	v_mfma_f32_16x16x32_bf16 v[0:3], v[242:245], v[64:67], v[0:3]
	v_mfma_f32_16x16x32_bf16 v[4:7], v[246:249], v[68:71], v[4:7]
	v_mfma_f32_16x16x32_bf16 v[8:11], v[250:253], v[72:75], v[8:11]
	v_mfma_f32_16x16x32_bf16 v[12:15], v[242:245], v[76:79], v[12:15]
	v_mfma_f32_16x16x32_bf16 v[16:19], v[246:249], v[80:83], v[16:19]
	v_mfma_f32_16x16x32_bf16 v[20:23], v[250:253], v[84:87], v[20:23]
	v_mfma_f32_16x16x32_bf16 v[24:27], v[242:245], v[88:91], v[24:27]
	v_mfma_f32_16x16x32_bf16 v[28:31], v[246:249], v[92:95], v[28:31]
	v_mfma_f32_16x16x32_bf16 v[32:35], v[250:253], v[194:197], v[32:35]
	v_mfma_f32_16x16x32_bf16 v[36:39], v[242:245], v[198:201], v[36:39]
	v_mfma_f32_16x16x32_bf16 v[40:43], v[246:249], v[202:205], v[40:43]
	v_mfma_f32_16x16x32_bf16 v[44:47], v[250:253], v[206:209], v[44:47]
	s_nop 7
	global_load_dwordx4 v[64:67], v[164:165], off
	global_load_dwordx4 v[68:71], v[166:167], off
	global_load_dwordx4 v[72:75], v[168:169], off
	global_load_dwordx4 v[76:79], v[170:171], off
	global_load_dwordx4 v[80:83], v[172:173], off
	global_load_dwordx4 v[84:87], v[174:175], off
	global_load_dwordx4 v[88:91], v[176:177], off
	ds_read_b128 v[92:95], v178 offset:384
	ds_read_b128 v[194:197], v178 offset:448
	ds_read_b128 v[198:201], v178 offset:512
	ds_read_b128 v[202:205], v178 offset:576
	s_waitcnt vmcnt(12) lgkmcnt(3)
	v_mfma_f32_16x16x32_bf16 v[48:51], v[92:95], v[48:51], 0
	v_mfma_f32_16x16x32_bf16 v[52:55], v[92:95], v[52:55], 0
	v_mfma_f32_16x16x32_bf16 v[56:59], v[92:95], v[56:59], 0
	v_mfma_f32_16x16x32_bf16 v[60:63], v[92:95], v[60:63], 0
	s_waitcnt vmcnt(8) lgkmcnt(2)
	v_mfma_f32_16x16x32_bf16 v[48:51], v[194:197], v[210:213], v[48:51]
	v_mfma_f32_16x16x32_bf16 v[52:55], v[194:197], v[214:217], v[52:55]
	v_mfma_f32_16x16x32_bf16 v[56:59], v[194:197], v[218:221], v[56:59]
	v_mfma_f32_16x16x32_bf16 v[60:63], v[194:197], v[222:225], v[60:63]
	s_waitcnt vmcnt(7) lgkmcnt(1)
	v_mfma_f32_16x16x32_bf16 v[48:51], v[198:201], v[226:229], v[48:51]
	s_waitcnt vmcnt(4)
	v_mfma_f32_16x16x32_bf16 v[52:55], v[198:201], v[64:67], v[52:55]
	v_mfma_f32_16x16x32_bf16 v[56:59], v[198:201], v[68:71], v[56:59]
	v_mfma_f32_16x16x32_bf16 v[60:63], v[198:201], v[72:75], v[60:63]
	s_waitcnt vmcnt(0) lgkmcnt(0)
	v_mfma_f32_16x16x32_bf16 v[48:51], v[202:205], v[76:79], v[48:51]
	v_mfma_f32_16x16x32_bf16 v[52:55], v[202:205], v[80:83], v[52:55]
	v_mfma_f32_16x16x32_bf16 v[56:59], v[202:205], v[84:87], v[56:59]
	v_mfma_f32_16x16x32_bf16 v[60:63], v[202:205], v[88:91], v[60:63]
	v_or_b32_e32 v193, s6, v185
	s_mov_b32 s40, 0
